# residual epilogues (out/down projections): flat->global, three row groups of base loads kept in flight with counted vmcnt instead of a full wait per group
# speedup vs baseline: 1.0131x; 1.0055x over previous
;     __device__ __forceinline__ void operator()(const f32x4 (&acc)[2][2][4][2], const Unit& u, int wr, int wc, int fr, int fq) const {
;         const int row0 = 256 * u.pm; const bool isctx = row0 >= NLAT; const int mb = isctx ? 4 : (row0 >> 13);
;         const float* bp = isctx ? base_ctx + (size_t)(row0 - NLAT) * 1024 : base_lat + (size_t)row0 * 1024;
;         float* op = isctx ? out_ctx + (size_t)(row0 - NLAT) * 1024 : out_lat + (size_t)row0 * 1024;
;         const float* mp = mod + mb * 6144 + moff;
;         f32x4 mv[2][2];
; #pragma unroll
;         for (int bj = 0; bj < 2; ++bj)
; #pragma unroll
;             for (int n = 0; n < 2; ++n) mv[bj][n] = *(const f32x4*)(mp + 256 * u.pn + 128 * bj + 32 * wc + 8 * fq + 4 * n);
;         const size_t cb0 = (size_t)256 * u.pn + 32 * wc + 8 * fq;
;         if (u.mode > 0) {
;             float* pp = part + (size_t)(u.mode - 1) * NCTX * 1024 + (size_t)(row0 - NLAT) * 1024;
;             FOR_AI_M {
;                 const size_t ro = (size_t)(128 * ai + 64 * wr + 16 * m + fr) * 1024 + cb0;
; #pragma unroll
;                 for (int bj = 0; bj < 2; ++bj)
; #pragma unroll
;                     for (int n = 0; n < 2; ++n) *(f32x4*)(pp + ro + 128 * bj + 4 * n) = mv[bj][n] * acc[ai][bj][m][n];
;             }
;             return;
;         }
;         f32x4 pre[2][2][2];
; #pragma unroll
;         for (int bj = 0; bj < 2; ++bj)
; #pragma unroll
;             for (int n = 0; n < 2; ++n) pre[0][bj][n] = *(const f32x4*)(bp + (size_t)(64 * wr + fr) * 1024 + cb0 + 128 * bj + 4 * n);
; #pragma unroll
;         for (int g = 0; g < 8; ++g) {
;             const int ai = g >> 2, m = g & 3;
;             const size_t ro = (size_t)(128 * ai + 64 * wr + 16 * m + fr) * 1024 + cb0;
;             if (g + 1 < 8) {
;                 const size_t rn = (size_t)(128 * ((g + 1) >> 2) + 64 * wr + 16 * ((g + 1) & 3) + fr) * 1024 + cb0;
; #pragma unroll
;                 for (int bj = 0; bj < 2; ++bj)
; #pragma unroll
;                     for (int n = 0; n < 2; ++n) pre[(g + 1) & 1][bj][n] = *(const f32x4*)(bp + rn + 128 * bj + 4 * n);
;             }
;             asm volatile("" ::: "memory");
; #pragma unroll
;             for (int bj = 0; bj < 2; ++bj)
; #pragma unroll
;                 for (int n = 0; n < 2; ++n) *(f32x4*)(op + ro + 128 * bj + 4 * n) = pre[g & 1][bj][n] + mv[bj][n] * acc[ai][bj][m][n];
.LBB0_67:
	s_min_i32 s2, s96, 0x80
	s_lshr_b32 s2, s2, 5
	s_mulk_i32 s2, 0x1800
	s_ashr_i32 s3, s2, 31
	s_lshl_b32 s18, s96, 8
	s_lshl_b64 s[2:3], s[2:3], 2
	v_readlane_b32 s8, v254, 44
	s_add_u32 s17, s8, s2
	v_readlane_b32 s2, v254, 46
	s_addc_u32 s19, s2, s3
	s_lshl_b32 s2, s16, 8
	s_ashr_i32 s3, s2, 31
	s_lshl_b64 s[2:3], s[2:3], 2
	s_add_u32 s2, s17, s2
	v_mov_b32_e32 v128, v191
	v_mov_b32_e32 v146, v190
	s_addc_u32 s3, s19, s3
	v_readlane_b32 s8, v255, 3
	s_add_u32 s2, s2, s8
	v_lshlrev_b32_e32 v144, 3, v128
	s_addc_u32 s3, s3, 0
	v_ashrrev_i32_e32 v145, 31, v144
	v_lshl_add_u64 v[128:129], v[144:145], 2, s[2:3]
	s_mov_b64 s[2:3], 0x5000
	v_lshl_add_u64 v[130:131], v[128:129], 0, s[2:3]
	s_movk_i32 s2, 0x5000
	v_add_co_u32_e32 v128, vcc, s2, v128
	s_ashr_i32 s17, s16, 31
	s_nop 0
	v_addc_co_u32_e32 v129, vcc, 0, v129, vcc
	global_load_dwordx4 v[136:139], v[130:131], off offset:16
	global_load_dwordx4 v[132:135], v[130:131], off offset:512
	global_load_dwordx4 v[140:143], v[128:129], off
	s_nop 0
	global_load_dwordx4 v[128:131], v[130:131], off offset:528
	v_readlane_b32 s8, v254, 63
	s_lshl_b64 s[2:3], s[16:17], 8
	v_readlane_b32 s9, v255, 0
	s_or_b64 s[2:3], s[2:3], s[8:9]
	v_lshl_add_u64 v[182:183], s[2:3], 0, v[144:145]
	v_readlane_b32 s2, v254, 61
	s_cmp_lt_i32 s64, 1
	s_mov_b64 s[16:17], -1
	v_add_u32_e32 v180, s2, v146
	v_add_u32_e32 v178, 16, v180
	v_add_u32_e32 v176, 32, v180
	v_add_u32_e32 v174, 48, v180
	v_add_u32_e32 v172, 0x80, v180
	v_add_u32_e32 v170, 0x90, v180
	v_ashrrev_i32_e32 v181, 31, v180
	v_ashrrev_i32_e32 v179, 31, v178
	v_ashrrev_i32_e32 v177, 31, v176
	v_ashrrev_i32_e32 v175, 31, v174
	v_ashrrev_i32_e32 v173, 31, v172
	v_ashrrev_i32_e32 v171, 31, v170
	v_add_u32_e32 v168, 0xa0, v180
	v_add_u32_e32 v166, 0xb0, v180
	s_cbranch_scc0 .LBB0_70
	s_add_i32 s2, s18, 0xffff8000
	s_ashr_i32 s3, s18, 31
	s_mov_b32 s16, s11
	s_mov_b32 s17, s10
	v_readlane_b32 s8, v251, 0
	s_cmpk_gt_i32 s96, 0x7f
	v_readlane_b32 s11, v251, 3
	v_readlane_b32 s15, v251, 7
	v_readlane_b32 s8, v254, 49
	v_readlane_b32 s10, v251, 2
	v_readlane_b32 s14, v251, 6
	s_mov_b32 s11, s16
	s_cselect_b32 s16, s8, s15
	v_readlane_b32 s8, v254, 47
	s_cselect_b32 s3, 0, s3
	s_cselect_b32 s2, s2, s18
	s_mov_b32 s10, s17
	s_cselect_b32 s17, s8, s14
	s_lshl_b64 s[2:3], s[2:3], 12
	s_add_u32 s2, s17, s2
	s_addc_u32 s3, s16, s3
	v_ashrrev_i32_e32 v181, 31, v180
	v_ashrrev_i32_e32 v179, 31, v178
	v_ashrrev_i32_e32 v177, 31, v176
	v_ashrrev_i32_e32 v175, 31, v174
	v_ashrrev_i32_e32 v173, 31, v172
	v_ashrrev_i32_e32 v171, 31, v170
	v_ashrrev_i32_e32 v169, 31, v168
	v_ashrrev_i32_e32 v167, 31, v166
	v_lshlrev_b64 v[186:187], 2, v[182:183]
	v_lshl_add_u64 v[188:189], s[2:3], 0, v[186:187]
	v_lshl_add_u64 v[186:187], s[2:3], 0, v[186:187]
	v_lshlrev_b64 v[200:201], 12, v[180:181]
	v_lshl_add_u64 v[200:201], v[186:187], 0, v[200:201]
	global_load_dwordx4 v[144:147], v[200:201], off
	global_load_dwordx4 v[148:151], v[200:201], off offset:16
	global_load_dwordx4 v[152:155], v[200:201], off offset:512
	global_load_dwordx4 v[156:159], v[200:201], off offset:528
	v_lshlrev_b64 v[200:201], 12, v[178:179]
	v_lshl_add_u64 v[200:201], v[186:187], 0, v[200:201]
	global_load_dwordx4 v[202:205], v[200:201], off
	global_load_dwordx4 v[206:209], v[200:201], off offset:16
	global_load_dwordx4 v[210:213], v[200:201], off offset:512
	global_load_dwordx4 v[214:217], v[200:201], off offset:528
	v_lshlrev_b64 v[200:201], 12, v[176:177]
	v_lshl_add_u64 v[200:201], v[186:187], 0, v[200:201]
	global_load_dwordx4 v[218:221], v[200:201], off
	global_load_dwordx4 v[222:225], v[200:201], off offset:16
	global_load_dwordx4 v[230:233], v[200:201], off offset:512
	global_load_dwordx4 v[234:237], v[200:201], off offset:528
	v_lshlrev_b64 v[248:249], 12, v[180:181]
	v_lshl_add_u64 v[248:249], v[188:189], 0, v[248:249]
	s_waitcnt vmcnt(8)
	v_pk_fma_f32 v[144:145], v[124:125], v[140:141], v[144:145]
	v_pk_fma_f32 v[146:147], v[126:127], v[142:143], v[146:147]
	v_pk_fma_f32 v[148:149], v[120:121], v[136:137], v[148:149]
	v_pk_fma_f32 v[150:151], v[122:123], v[138:139], v[150:151]
	v_pk_fma_f32 v[152:153], v[112:113], v[132:133], v[152:153]
	v_pk_fma_f32 v[154:155], v[114:115], v[134:135], v[154:155]
	v_pk_fma_f32 v[156:157], v[104:105], v[128:129], v[156:157]
	v_pk_fma_f32 v[158:159], v[106:107], v[130:131], v[158:159]
	global_store_dwordx4 v[248:249], v[144:147], off
	global_store_dwordx4 v[248:249], v[148:151], off offset:16
	global_store_dwordx4 v[248:249], v[152:155], off offset:512
	global_store_dwordx4 v[248:249], v[156:159], off offset:528
	v_lshlrev_b64 v[200:201], 12, v[174:175]
	v_lshl_add_u64 v[200:201], v[186:187], 0, v[200:201]
	global_load_dwordx4 v[144:147], v[200:201], off
	global_load_dwordx4 v[148:151], v[200:201], off offset:16
	global_load_dwordx4 v[152:155], v[200:201], off offset:512
	global_load_dwordx4 v[156:159], v[200:201], off offset:528
	v_lshlrev_b64 v[248:249], 12, v[178:179]
	v_lshl_add_u64 v[248:249], v[188:189], 0, v[248:249]
	s_waitcnt vmcnt(12)
	v_pk_fma_f32 v[202:203], v[116:117], v[140:141], v[202:203]
	v_pk_fma_f32 v[204:205], v[118:119], v[142:143], v[204:205]
	v_pk_fma_f32 v[206:207], v[108:109], v[136:137], v[206:207]
	v_pk_fma_f32 v[208:209], v[110:111], v[138:139], v[208:209]
	v_pk_fma_f32 v[210:211], v[96:97], v[132:133], v[210:211]
	v_pk_fma_f32 v[212:213], v[98:99], v[134:135], v[212:213]
	v_pk_fma_f32 v[214:215], v[88:89], v[128:129], v[214:215]
	v_pk_fma_f32 v[216:217], v[90:91], v[130:131], v[216:217]
	global_store_dwordx4 v[248:249], v[202:205], off
	global_store_dwordx4 v[248:249], v[206:209], off offset:16
	global_store_dwordx4 v[248:249], v[210:213], off offset:512
	global_store_dwordx4 v[248:249], v[214:217], off offset:528
	v_lshlrev_b64 v[200:201], 12, v[172:173]
	v_lshl_add_u64 v[200:201], v[186:187], 0, v[200:201]
	global_load_dwordx4 v[202:205], v[200:201], off
	global_load_dwordx4 v[206:209], v[200:201], off offset:16
	global_load_dwordx4 v[210:213], v[200:201], off offset:512
	global_load_dwordx4 v[214:217], v[200:201], off offset:528
	v_lshlrev_b64 v[248:249], 12, v[176:177]
	v_lshl_add_u64 v[248:249], v[188:189], 0, v[248:249]
	s_waitcnt vmcnt(16)
;     __device__ __forceinline__ void operator()(const f32x4 (&acc)[2][2][4][2], const Unit& u, int wr, int wc, int fr, int fq) const {
;     ...
;         for (int g = 0; g < 8; ++g) {
;             const int ai = g >> 2, m = g & 3;
;             const size_t ro = (size_t)(128 * ai + 64 * wr + 16 * m + fr) * 1024 + cb0;
;             if (g + 1 < 8) {
;                 const size_t rn = (size_t)(128 * ((g + 1) >> 2) + 64 * wr + 16 * ((g + 1) & 3) + fr) * 1024 + cb0;
; #pragma unroll
;                 for (int bj = 0; bj < 2; ++bj)
; #pragma unroll
;                     for (int n = 0; n < 2; ++n) pre[(g + 1) & 1][bj][n] = *(const f32x4*)(bp + rn + 128 * bj + 4 * n);
;             }
;             asm volatile("" ::: "memory");
; #pragma unroll
;             for (int bj = 0; bj < 2; ++bj)
; #pragma unroll
;                 for (int n = 0; n < 2; ++n) *(f32x4*)(op + ro + 128 * bj + 4 * n) = pre[g & 1][bj][n] + mv[bj][n] * acc[ai][bj][m][n];
	v_pk_fma_f32 v[218:219], v[100:101], v[140:141], v[218:219]
	v_pk_fma_f32 v[220:221], v[102:103], v[142:143], v[220:221]
	v_pk_fma_f32 v[222:223], v[92:93], v[136:137], v[222:223]
	v_pk_fma_f32 v[224:225], v[94:95], v[138:139], v[224:225]
	v_pk_fma_f32 v[230:231], v[80:81], v[132:133], v[230:231]
	v_pk_fma_f32 v[232:233], v[82:83], v[134:135], v[232:233]
	v_pk_fma_f32 v[234:235], v[72:73], v[128:129], v[234:235]
	v_pk_fma_f32 v[236:237], v[74:75], v[130:131], v[236:237]
	global_store_dwordx4 v[248:249], v[218:221], off
	global_store_dwordx4 v[248:249], v[222:225], off offset:16
	global_store_dwordx4 v[248:249], v[230:233], off offset:512
	global_store_dwordx4 v[248:249], v[234:237], off offset:528
	v_lshlrev_b64 v[200:201], 12, v[170:171]
	v_lshl_add_u64 v[200:201], v[186:187], 0, v[200:201]
	global_load_dwordx4 v[218:221], v[200:201], off
	global_load_dwordx4 v[222:225], v[200:201], off offset:16
	global_load_dwordx4 v[230:233], v[200:201], off offset:512
	global_load_dwordx4 v[234:237], v[200:201], off offset:528
	v_lshlrev_b64 v[248:249], 12, v[174:175]
	v_lshl_add_u64 v[248:249], v[188:189], 0, v[248:249]
	s_waitcnt vmcnt(16)
	v_pk_fma_f32 v[144:145], v[84:85], v[140:141], v[144:145]
	v_pk_fma_f32 v[146:147], v[86:87], v[142:143], v[146:147]
	v_pk_fma_f32 v[148:149], v[76:77], v[136:137], v[148:149]
	v_pk_fma_f32 v[150:151], v[78:79], v[138:139], v[150:151]
	v_pk_fma_f32 v[152:153], v[68:69], v[132:133], v[152:153]
	v_pk_fma_f32 v[154:155], v[70:71], v[134:135], v[154:155]
	v_pk_fma_f32 v[156:157], v[64:65], v[128:129], v[156:157]
	v_pk_fma_f32 v[158:159], v[66:67], v[130:131], v[158:159]
	global_store_dwordx4 v[248:249], v[144:147], off
	global_store_dwordx4 v[248:249], v[148:151], off offset:16
	global_store_dwordx4 v[248:249], v[152:155], off offset:512
	global_store_dwordx4 v[248:249], v[156:159], off offset:528
	v_lshlrev_b64 v[200:201], 12, v[168:169]
	v_lshl_add_u64 v[200:201], v[186:187], 0, v[200:201]
	global_load_dwordx4 v[144:147], v[200:201], off
	global_load_dwordx4 v[148:151], v[200:201], off offset:16
	global_load_dwordx4 v[152:155], v[200:201], off offset:512
	global_load_dwordx4 v[156:159], v[200:201], off offset:528
	v_lshlrev_b64 v[248:249], 12, v[172:173]
	v_lshl_add_u64 v[248:249], v[188:189], 0, v[248:249]
	s_waitcnt vmcnt(16)
	v_pk_fma_f32 v[202:203], v[60:61], v[140:141], v[202:203]
	v_pk_fma_f32 v[204:205], v[62:63], v[142:143], v[204:205]
	v_pk_fma_f32 v[206:207], v[56:57], v[136:137], v[206:207]
	v_pk_fma_f32 v[208:209], v[58:59], v[138:139], v[208:209]
	v_pk_fma_f32 v[210:211], v[48:49], v[132:133], v[210:211]
	v_pk_fma_f32 v[212:213], v[50:51], v[134:135], v[212:213]
	v_pk_fma_f32 v[214:215], v[40:41], v[128:129], v[214:215]
	v_pk_fma_f32 v[216:217], v[42:43], v[130:131], v[216:217]
	global_store_dwordx4 v[248:249], v[202:205], off
	global_store_dwordx4 v[248:249], v[206:209], off offset:16
	global_store_dwordx4 v[248:249], v[210:213], off offset:512
	global_store_dwordx4 v[248:249], v[214:217], off offset:528
	v_lshlrev_b64 v[200:201], 12, v[166:167]
	v_lshl_add_u64 v[200:201], v[186:187], 0, v[200:201]
	global_load_dwordx4 v[202:205], v[200:201], off
	global_load_dwordx4 v[206:209], v[200:201], off offset:16
	global_load_dwordx4 v[210:213], v[200:201], off offset:512
	global_load_dwordx4 v[214:217], v[200:201], off offset:528
	v_lshlrev_b64 v[248:249], 12, v[170:171]
	v_lshl_add_u64 v[248:249], v[188:189], 0, v[248:249]
	s_waitcnt vmcnt(16)
	v_pk_fma_f32 v[218:219], v[52:53], v[140:141], v[218:219]
	v_pk_fma_f32 v[220:221], v[54:55], v[142:143], v[220:221]
	v_pk_fma_f32 v[222:223], v[44:45], v[136:137], v[222:223]
	v_pk_fma_f32 v[224:225], v[46:47], v[138:139], v[224:225]
	v_pk_fma_f32 v[230:231], v[32:33], v[132:133], v[230:231]
	v_pk_fma_f32 v[232:233], v[34:35], v[134:135], v[232:233]
	v_pk_fma_f32 v[234:235], v[24:25], v[128:129], v[234:235]
	v_pk_fma_f32 v[236:237], v[26:27], v[130:131], v[236:237]
	global_store_dwordx4 v[248:249], v[218:221], off
	global_store_dwordx4 v[248:249], v[222:225], off offset:16
	global_store_dwordx4 v[248:249], v[230:233], off offset:512
	global_store_dwordx4 v[248:249], v[234:237], off offset:528
	v_lshlrev_b64 v[248:249], 12, v[168:169]
	v_lshl_add_u64 v[248:249], v[188:189], 0, v[248:249]
	s_waitcnt vmcnt(12)
	v_pk_fma_f32 v[144:145], v[36:37], v[140:141], v[144:145]
	v_pk_fma_f32 v[146:147], v[38:39], v[142:143], v[146:147]
	v_pk_fma_f32 v[148:149], v[28:29], v[136:137], v[148:149]
	v_pk_fma_f32 v[150:151], v[30:31], v[138:139], v[150:151]
	v_pk_fma_f32 v[152:153], v[16:17], v[132:133], v[152:153]
	v_pk_fma_f32 v[154:155], v[18:19], v[134:135], v[154:155]
	v_pk_fma_f32 v[156:157], v[8:9], v[128:129], v[156:157]
	v_pk_fma_f32 v[158:159], v[10:11], v[130:131], v[158:159]
	global_store_dwordx4 v[248:249], v[144:147], off
	global_store_dwordx4 v[248:249], v[148:151], off offset:16
	global_store_dwordx4 v[248:249], v[152:155], off offset:512
	global_store_dwordx4 v[248:249], v[156:159], off offset:528
	v_lshlrev_b64 v[184:185], 12, v[166:167]
	v_lshl_add_u64 v[184:185], v[188:189], 0, v[184:185]
	s_waitcnt vmcnt(8)
	v_pk_fma_f32 v[202:203], v[20:21], v[140:141], v[202:203]
	v_pk_fma_f32 v[204:205], v[22:23], v[142:143], v[204:205]
	v_pk_fma_f32 v[206:207], v[12:13], v[136:137], v[206:207]
	v_pk_fma_f32 v[208:209], v[14:15], v[138:139], v[208:209]
	v_pk_fma_f32 v[210:211], v[4:5], v[132:133], v[210:211]
	v_pk_fma_f32 v[212:213], v[6:7], v[134:135], v[212:213]
	v_pk_fma_f32 v[214:215], v[0:1], v[128:129], v[214:215]
	v_pk_fma_f32 v[216:217], v[2:3], v[130:131], v[216:217]
	global_store_dwordx4 v[184:185], v[202:205], off
	global_store_dwordx4 v[184:185], v[206:209], off offset:16
	global_store_dwordx4 v[184:185], v[210:213], off offset:512
	s_nop 0
	v_mov_b32_e32 v144, v214
	v_mov_b32_e32 v145, v215
	v_mov_b32_e32 v146, v216
	v_mov_b32_e32 v147, v217
	s_cbranch_execz .LBB0_71

;     __device__ __forceinline__ void operator()(const f32x4 (&acc)[2][2][4][2], const Unit& u, int wr, int wc, int fr, int fq) const {
;         const int row0 = 256 * u.pm; const bool isctx = row0 >= NLAT; const int mb = isctx ? 4 : (row0 >> 13);
;         const float* bp = isctx ? base_ctx + (size_t)(row0 - NLAT) * 1024 : base_lat + (size_t)row0 * 1024;
;         float* op = isctx ? out_ctx + (size_t)(row0 - NLAT) * 1024 : out_lat + (size_t)row0 * 1024;
;         const float* mp = mod + mb * 6144 + moff;
;         f32x4 mv[2][2];
; #pragma unroll
;         for (int bj = 0; bj < 2; ++bj)
; #pragma unroll
;             for (int n = 0; n < 2; ++n) mv[bj][n] = *(const f32x4*)(mp + 256 * u.pn + 128 * bj + 32 * wc + 8 * fq + 4 * n);
;         const size_t cb0 = (size_t)256 * u.pn + 32 * wc + 8 * fq;
;         if (u.mode > 0) {
;             float* pp = part + (size_t)(u.mode - 1) * NCTX * 1024 + (size_t)(row0 - NLAT) * 1024;
;             FOR_AI_M {
;                 const size_t ro = (size_t)(128 * ai + 64 * wr + 16 * m + fr) * 1024 + cb0;
; #pragma unroll
;                 for (int bj = 0; bj < 2; ++bj)
; #pragma unroll
;                     for (int n = 0; n < 2; ++n) *(f32x4*)(pp + ro + 128 * bj + 4 * n) = mv[bj][n] * acc[ai][bj][m][n];
;             }
;             return;
;         }
;         f32x4 pre[2][2][2];
; #pragma unroll
;         for (int bj = 0; bj < 2; ++bj)
; #pragma unroll
;             for (int n = 0; n < 2; ++n) pre[0][bj][n] = *(const f32x4*)(bp + (size_t)(64 * wr + fr) * 1024 + cb0 + 128 * bj + 4 * n);
; #pragma unroll
;         for (int g = 0; g < 8; ++g) {
;             const int ai = g >> 2, m = g & 3;
;             const size_t ro = (size_t)(128 * ai + 64 * wr + 16 * m + fr) * 1024 + cb0;
;             if (g + 1 < 8) {
;                 const size_t rn = (size_t)(128 * ((g + 1) >> 2) + 64 * wr + 16 * ((g + 1) & 3) + fr) * 1024 + cb0;
; #pragma unroll
;                 for (int bj = 0; bj < 2; ++bj)
; #pragma unroll
;                     for (int n = 0; n < 2; ++n) pre[(g + 1) & 1][bj][n] = *(const f32x4*)(bp + rn + 128 * bj + 4 * n);
;             }
;             asm volatile("" ::: "memory");
; #pragma unroll
;             for (int bj = 0; bj < 2; ++bj)
; #pragma unroll
;                 for (int n = 0; n < 2; ++n) *(f32x4*)(op + ro + 128 * bj + 4 * n) = pre[g & 1][bj][n] + mv[bj][n] * acc[ai][bj][m][n];
.LBB0_201:
	s_min_i32 s21, s18, 0x80
	s_lshr_b32 s21, s21, 5
	s_mul_i32 s26, s21, 0x1800
	s_ashr_i32 s27, s26, 31
	s_lshl_b32 s24, s18, 8
	s_lshl_b64 s[26:27], s[26:27], 2
	v_readlane_b32 s8, v254, 44
	s_add_u32 s21, s8, s26
	v_readlane_b32 s8, v254, 46
	s_addc_u32 s25, s8, s27
	s_lshl_b32 s26, s20, 8
	s_ashr_i32 s27, s26, 31
	s_lshl_b64 s[26:27], s[26:27], 2
	s_add_u32 s21, s21, s26
	v_mov_b32_e32 v128, v198
	v_mov_b32_e32 v146, v197
	s_addc_u32 s25, s25, s27
	s_add_u32 s26, s21, s1
	v_lshlrev_b32_e32 v144, 3, v128
	s_addc_u32 s27, s25, 0
	v_ashrrev_i32_e32 v145, 31, v144
	v_lshl_add_u64 v[128:129], v[144:145], 2, s[26:27]
	s_mov_b64 s[26:27], 0x2000
	s_movk_i32 s8, 0x2000
	v_lshl_add_u64 v[130:131], v[128:129], 0, s[26:27]
	v_add_co_u32_e32 v128, vcc, s8, v128
	s_ashr_i32 s21, s20, 31
	s_nop 0
	v_addc_co_u32_e32 v129, vcc, 0, v129, vcc
	global_load_dwordx4 v[136:139], v[130:131], off offset:16
	global_load_dwordx4 v[132:135], v[130:131], off offset:512
	global_load_dwordx4 v[140:143], v[128:129], off
	s_nop 0
	global_load_dwordx4 v[128:131], v[130:131], off offset:528
	v_readlane_b32 s8, v254, 61
	s_lshl_b64 s[20:21], s[20:21], 8
	v_readlane_b32 s9, v254, 62
	s_or_b64 s[20:21], s[20:21], s[8:9]
	v_add_u32_e32 v180, s97, v146
	v_lshl_add_u64 v[182:183], s[20:21], 0, v[144:145]
	s_mov_b64 s[20:21], -1
	s_cmp_lt_i32 s94, 1
	v_ashrrev_i32_e32 v181, 31, v180
	v_add_u32_e32 v178, 16, v180
	v_add_u32_e32 v176, 32, v180
	v_add_u32_e32 v174, 48, v180
	v_add_u32_e32 v172, 0x80, v180
	v_add_u32_e32 v170, 0x90, v180
	v_add_u32_e32 v168, 0xa0, v180
	v_add_u32_e32 v166, 0xb0, v180
	v_readlane_b32 s95, v253, 26
	s_mov_b32 s64, 0x3f22f983
	s_cbranch_scc0 .LBB0_204
	s_add_i32 s20, s24, 0xffff8000
	s_ashr_i32 s21, s24, 31
	v_readlane_b32 s8, v251, 0
	s_cmpk_gt_i32 s18, 0x7f
	v_readlane_b32 s15, v251, 7
	v_readlane_b32 s8, v254, 49
	v_readlane_b32 s9, v251, 1
	v_readlane_b32 s14, v251, 6
	s_cselect_b32 s18, s8, s15
	v_readlane_b32 s8, v254, 47
	s_cselect_b32 s25, s8, s14
	v_readlane_b32 s8, v254, 22
	v_readlane_b32 s9, v254, 60
	s_cselect_b32 s21, 0, s21
	s_cselect_b32 s20, s20, s24
	s_cselect_b32 s28, s9, s8
	v_readlane_b32 s8, v254, 23
	v_readlane_b32 s9, v254, 53
	s_cselect_b32 s29, s9, s8
	s_lshl_b64 s[20:21], s[20:21], 12
	s_add_u32 s26, s25, s20
	s_addc_u32 s27, s18, s21
	s_add_u32 s20, s29, s20
	s_addc_u32 s21, s28, s21
	v_ashrrev_i32_e32 v181, 31, v180
	v_ashrrev_i32_e32 v179, 31, v178
	v_ashrrev_i32_e32 v177, 31, v176
	v_ashrrev_i32_e32 v175, 31, v174
	v_ashrrev_i32_e32 v173, 31, v172
	v_ashrrev_i32_e32 v171, 31, v170
	v_ashrrev_i32_e32 v169, 31, v168
	v_ashrrev_i32_e32 v167, 31, v166
	v_lshlrev_b64 v[186:187], 2, v[182:183]
	v_lshl_add_u64 v[188:189], s[26:27], 0, v[186:187]
	v_lshl_add_u64 v[186:187], s[20:21], 0, v[186:187]
	v_lshlrev_b64 v[184:185], 12, v[180:181]
	v_lshl_add_u64 v[184:185], v[186:187], 0, v[184:185]
	global_load_dwordx4 v[144:147], v[184:185], off
	global_load_dwordx4 v[148:151], v[184:185], off offset:16
	global_load_dwordx4 v[152:155], v[184:185], off offset:512
	global_load_dwordx4 v[156:159], v[184:185], off offset:528
	v_lshlrev_b64 v[184:185], 12, v[178:179]
	v_lshl_add_u64 v[184:185], v[186:187], 0, v[184:185]
	global_load_dwordx4 v[202:205], v[184:185], off
	global_load_dwordx4 v[206:209], v[184:185], off offset:16
	global_load_dwordx4 v[210:213], v[184:185], off offset:512
	global_load_dwordx4 v[214:217], v[184:185], off offset:528
	v_lshlrev_b64 v[184:185], 12, v[176:177]
	v_lshl_add_u64 v[184:185], v[186:187], 0, v[184:185]
	global_load_dwordx4 v[218:221], v[184:185], off
	global_load_dwordx4 v[222:225], v[184:185], off offset:16
	global_load_dwordx4 v[230:233], v[184:185], off offset:512
	global_load_dwordx4 v[234:237], v[184:185], off offset:528
	v_lshlrev_b64 v[248:249], 12, v[180:181]
	v_lshl_add_u64 v[248:249], v[188:189], 0, v[248:249]
	s_waitcnt vmcnt(8)
	v_pk_fma_f32 v[144:145], v[124:125], v[140:141], v[144:145]
	v_pk_fma_f32 v[146:147], v[126:127], v[142:143], v[146:147]
	v_pk_fma_f32 v[148:149], v[120:121], v[136:137], v[148:149]
	v_pk_fma_f32 v[150:151], v[122:123], v[138:139], v[150:151]
	v_pk_fma_f32 v[152:153], v[116:117], v[132:133], v[152:153]
	v_pk_fma_f32 v[154:155], v[118:119], v[134:135], v[154:155]
	v_pk_fma_f32 v[156:157], v[104:105], v[128:129], v[156:157]
	v_pk_fma_f32 v[158:159], v[106:107], v[130:131], v[158:159]
	global_store_dwordx4 v[248:249], v[144:147], off
	global_store_dwordx4 v[248:249], v[148:151], off offset:16
	global_store_dwordx4 v[248:249], v[152:155], off offset:512
	global_store_dwordx4 v[248:249], v[156:159], off offset:528
	v_lshlrev_b64 v[184:185], 12, v[174:175]
	v_lshl_add_u64 v[184:185], v[186:187], 0, v[184:185]
	global_load_dwordx4 v[144:147], v[184:185], off
	global_load_dwordx4 v[148:151], v[184:185], off offset:16
	global_load_dwordx4 v[152:155], v[184:185], off offset:512
	global_load_dwordx4 v[156:159], v[184:185], off offset:528
	v_lshlrev_b64 v[248:249], 12, v[178:179]
	v_lshl_add_u64 v[248:249], v[188:189], 0, v[248:249]
	s_waitcnt vmcnt(12)
	v_pk_fma_f32 v[202:203], v[112:113], v[140:141], v[202:203]
	v_pk_fma_f32 v[204:205], v[114:115], v[142:143], v[204:205]
	v_pk_fma_f32 v[206:207], v[108:109], v[136:137], v[206:207]
	v_pk_fma_f32 v[208:209], v[110:111], v[138:139], v[208:209]
	v_pk_fma_f32 v[210:211], v[96:97], v[132:133], v[210:211]
	v_pk_fma_f32 v[212:213], v[98:99], v[134:135], v[212:213]
	v_pk_fma_f32 v[214:215], v[88:89], v[128:129], v[214:215]
	v_pk_fma_f32 v[216:217], v[90:91], v[130:131], v[216:217]
	global_store_dwordx4 v[248:249], v[202:205], off
	global_store_dwordx4 v[248:249], v[206:209], off offset:16
	global_store_dwordx4 v[248:249], v[210:213], off offset:512
	global_store_dwordx4 v[248:249], v[214:217], off offset:528
	v_lshlrev_b64 v[184:185], 12, v[172:173]
	v_lshl_add_u64 v[184:185], v[186:187], 0, v[184:185]
	global_load_dwordx4 v[202:205], v[184:185], off
	global_load_dwordx4 v[206:209], v[184:185], off offset:16
	global_load_dwordx4 v[210:213], v[184:185], off offset:512
	global_load_dwordx4 v[214:217], v[184:185], off offset:528
	v_lshlrev_b64 v[248:249], 12, v[176:177]
	v_lshl_add_u64 v[248:249], v[188:189], 0, v[248:249]
	s_waitcnt vmcnt(16)
;     __device__ __forceinline__ void operator()(const f32x4 (&acc)[2][2][4][2], const Unit& u, int wr, int wc, int fr, int fq) const {
;     ...
;         for (int g = 0; g < 8; ++g) {
;             const int ai = g >> 2, m = g & 3;
;             const size_t ro = (size_t)(128 * ai + 64 * wr + 16 * m + fr) * 1024 + cb0;
;             if (g + 1 < 8) {
;                 const size_t rn = (size_t)(128 * ((g + 1) >> 2) + 64 * wr + 16 * ((g + 1) & 3) + fr) * 1024 + cb0;
; #pragma unroll
;                 for (int bj = 0; bj < 2; ++bj)
; #pragma unroll
;                     for (int n = 0; n < 2; ++n) pre[(g + 1) & 1][bj][n] = *(const f32x4*)(bp + rn + 128 * bj + 4 * n);
;             }
;             asm volatile("" ::: "memory");
; #pragma unroll
;             for (int bj = 0; bj < 2; ++bj)
; #pragma unroll
;                 for (int n = 0; n < 2; ++n) *(f32x4*)(op + ro + 128 * bj + 4 * n) = pre[g & 1][bj][n] + mv[bj][n] * acc[ai][bj][m][n];
	v_pk_fma_f32 v[218:219], v[100:101], v[140:141], v[218:219]
	v_pk_fma_f32 v[220:221], v[102:103], v[142:143], v[220:221]
	v_pk_fma_f32 v[222:223], v[92:93], v[136:137], v[222:223]
	v_pk_fma_f32 v[224:225], v[94:95], v[138:139], v[224:225]
	v_pk_fma_f32 v[230:231], v[80:81], v[132:133], v[230:231]
	v_pk_fma_f32 v[232:233], v[82:83], v[134:135], v[232:233]
	v_pk_fma_f32 v[234:235], v[72:73], v[128:129], v[234:235]
	v_pk_fma_f32 v[236:237], v[74:75], v[130:131], v[236:237]
	global_store_dwordx4 v[248:249], v[218:221], off
	global_store_dwordx4 v[248:249], v[222:225], off offset:16
	global_store_dwordx4 v[248:249], v[230:233], off offset:512
	global_store_dwordx4 v[248:249], v[234:237], off offset:528
	v_lshlrev_b64 v[184:185], 12, v[170:171]
	v_lshl_add_u64 v[184:185], v[186:187], 0, v[184:185]
	global_load_dwordx4 v[218:221], v[184:185], off
	global_load_dwordx4 v[222:225], v[184:185], off offset:16
	global_load_dwordx4 v[230:233], v[184:185], off offset:512
	global_load_dwordx4 v[234:237], v[184:185], off offset:528
	v_lshlrev_b64 v[248:249], 12, v[174:175]
	v_lshl_add_u64 v[248:249], v[188:189], 0, v[248:249]
	s_waitcnt vmcnt(16)
	v_pk_fma_f32 v[144:145], v[84:85], v[140:141], v[144:145]
	v_pk_fma_f32 v[146:147], v[86:87], v[142:143], v[146:147]
	v_pk_fma_f32 v[148:149], v[76:77], v[136:137], v[148:149]
	v_pk_fma_f32 v[150:151], v[78:79], v[138:139], v[150:151]
	v_pk_fma_f32 v[152:153], v[68:69], v[132:133], v[152:153]
	v_pk_fma_f32 v[154:155], v[70:71], v[134:135], v[154:155]
	v_pk_fma_f32 v[156:157], v[64:65], v[128:129], v[156:157]
	v_pk_fma_f32 v[158:159], v[66:67], v[130:131], v[158:159]
	global_store_dwordx4 v[248:249], v[144:147], off
	global_store_dwordx4 v[248:249], v[148:151], off offset:16
	global_store_dwordx4 v[248:249], v[152:155], off offset:512
	global_store_dwordx4 v[248:249], v[156:159], off offset:528
	v_lshlrev_b64 v[184:185], 12, v[168:169]
	v_lshl_add_u64 v[184:185], v[186:187], 0, v[184:185]
	global_load_dwordx4 v[144:147], v[184:185], off
	global_load_dwordx4 v[148:151], v[184:185], off offset:16
	global_load_dwordx4 v[152:155], v[184:185], off offset:512
	global_load_dwordx4 v[156:159], v[184:185], off offset:528
	v_lshlrev_b64 v[248:249], 12, v[172:173]
	v_lshl_add_u64 v[248:249], v[188:189], 0, v[248:249]
	s_waitcnt vmcnt(16)
	v_pk_fma_f32 v[202:203], v[60:61], v[140:141], v[202:203]
	v_pk_fma_f32 v[204:205], v[62:63], v[142:143], v[204:205]
	v_pk_fma_f32 v[206:207], v[56:57], v[136:137], v[206:207]
	v_pk_fma_f32 v[208:209], v[58:59], v[138:139], v[208:209]
	v_pk_fma_f32 v[210:211], v[48:49], v[132:133], v[210:211]
	v_pk_fma_f32 v[212:213], v[50:51], v[134:135], v[212:213]
	v_pk_fma_f32 v[214:215], v[40:41], v[128:129], v[214:215]
	v_pk_fma_f32 v[216:217], v[42:43], v[130:131], v[216:217]
	global_store_dwordx4 v[248:249], v[202:205], off
	global_store_dwordx4 v[248:249], v[206:209], off offset:16
	global_store_dwordx4 v[248:249], v[210:213], off offset:512
	global_store_dwordx4 v[248:249], v[214:217], off offset:528
	v_lshlrev_b64 v[184:185], 12, v[166:167]
	v_lshl_add_u64 v[184:185], v[186:187], 0, v[184:185]
	global_load_dwordx4 v[202:205], v[184:185], off
	global_load_dwordx4 v[206:209], v[184:185], off offset:16
	global_load_dwordx4 v[210:213], v[184:185], off offset:512
	global_load_dwordx4 v[214:217], v[184:185], off offset:528
	v_lshlrev_b64 v[248:249], 12, v[170:171]
	v_lshl_add_u64 v[248:249], v[188:189], 0, v[248:249]
	s_waitcnt vmcnt(16)
	v_pk_fma_f32 v[218:219], v[52:53], v[140:141], v[218:219]
	v_pk_fma_f32 v[220:221], v[54:55], v[142:143], v[220:221]
	v_pk_fma_f32 v[222:223], v[44:45], v[136:137], v[222:223]
	v_pk_fma_f32 v[224:225], v[46:47], v[138:139], v[224:225]
	v_pk_fma_f32 v[230:231], v[32:33], v[132:133], v[230:231]
	v_pk_fma_f32 v[232:233], v[34:35], v[134:135], v[232:233]
	v_pk_fma_f32 v[234:235], v[24:25], v[128:129], v[234:235]
	v_pk_fma_f32 v[236:237], v[26:27], v[130:131], v[236:237]
	global_store_dwordx4 v[248:249], v[218:221], off
	global_store_dwordx4 v[248:249], v[222:225], off offset:16
	global_store_dwordx4 v[248:249], v[230:233], off offset:512
	global_store_dwordx4 v[248:249], v[234:237], off offset:528
	v_lshlrev_b64 v[248:249], 12, v[168:169]
	v_lshl_add_u64 v[248:249], v[188:189], 0, v[248:249]
	s_waitcnt vmcnt(12)
	v_pk_fma_f32 v[144:145], v[36:37], v[140:141], v[144:145]
	v_pk_fma_f32 v[146:147], v[38:39], v[142:143], v[146:147]
	v_pk_fma_f32 v[148:149], v[28:29], v[136:137], v[148:149]
	v_pk_fma_f32 v[150:151], v[30:31], v[138:139], v[150:151]
	v_pk_fma_f32 v[152:153], v[16:17], v[132:133], v[152:153]
	v_pk_fma_f32 v[154:155], v[18:19], v[134:135], v[154:155]
	v_pk_fma_f32 v[156:157], v[8:9], v[128:129], v[156:157]
	v_pk_fma_f32 v[158:159], v[10:11], v[130:131], v[158:159]
	global_store_dwordx4 v[248:249], v[144:147], off
	global_store_dwordx4 v[248:249], v[148:151], off offset:16
	global_store_dwordx4 v[248:249], v[152:155], off offset:512
	global_store_dwordx4 v[248:249], v[156:159], off offset:528
	v_lshlrev_b64 v[148:149], 12, v[166:167]
	v_lshl_add_u64 v[148:149], v[188:189], 0, v[148:149]
	s_waitcnt vmcnt(8)
	v_pk_fma_f32 v[202:203], v[20:21], v[140:141], v[202:203]
	v_pk_fma_f32 v[204:205], v[22:23], v[142:143], v[204:205]
	v_pk_fma_f32 v[206:207], v[12:13], v[136:137], v[206:207]
	v_pk_fma_f32 v[208:209], v[14:15], v[138:139], v[208:209]
	v_pk_fma_f32 v[210:211], v[4:5], v[132:133], v[210:211]
	v_pk_fma_f32 v[212:213], v[6:7], v[134:135], v[212:213]
	v_pk_fma_f32 v[214:215], v[0:1], v[128:129], v[214:215]
	v_pk_fma_f32 v[216:217], v[2:3], v[130:131], v[216:217]
	global_store_dwordx4 v[148:149], v[202:205], off
	global_store_dwordx4 v[148:149], v[206:209], off offset:16
	global_store_dwordx4 v[148:149], v[210:213], off offset:512
	s_nop 0
	v_mov_b32_e32 v144, v214
	v_mov_b32_e32 v145, v215
	v_mov_b32_e32 v146, v216
	v_mov_b32_e32 v147, v217
	s_cbranch_execz .LBB0_205
